# speedup vs baseline: 1.0057x; 1.0057x over previous
; __device__ __forceinline__ void partialSM(f32x16& p0, f32x16& p1, float& m_reg, float& mn, float& alpha) {
;     float pmax = p0[0];
; #pragma unroll
;     for (int r = 1; r < 16; ++r) pmax = fmaxf(pmax, p0[r]);
; #pragma unroll
;     for (int r = 0; r < 16; ++r) pmax = fmaxf(pmax, p1[r]);
;     { auto rr = __builtin_amdgcn_permlane32_swap(__float_as_uint(pmax), __float_as_uint(pmax), false, false);
;       pmax = fmaxf(__uint_as_float(rr[0]), __uint_as_float(rr[1])); }
;     constexpr float C2 = 1.4426950408889634f * ASCALE;
;     if (__builtin_expect(__all((pmax - m_reg) * ASCALE <= ATHR), 1)) { mn = m_reg; alpha = 1.f; }
;     else { mn = fmaxf(m_reg, pmax); alpha = __builtin_amdgcn_exp2f((m_reg - mn) * C2); m_reg = mn; }
; template <int VB>
; __device__ __forceinline__ void pv_tile(f32x16* o, int vb0, bf16x8 pa0, bf16x8 pa1, bf16x8 pa2, bf16x8 pa3) {
;     ...
;     PV_D0(0); PV_D0(1); PV_D0(2); PV_D0(3);
.LBB0_410:
	s_waitcnt lgkmcnt(4)
	v_mfma_f32_32x32x16_bf16 v[50:65], v[166:169], v[214:217], v[50:65]
	ds_read_b64_tr_b16 v[214:215], v194 offset:0x200
	ds_read_b64_tr_b16 v[216:217], v194 offset:0xa00
	v_max_f32_e32 v0, v82, v83
	v_mfma_f32_32x32x16_bf16 v[50:65], v[170:173], v[218:221], v[50:65]
	ds_read_b64_tr_b16 v[218:219], v194 offset:0x1200
	ds_read_b64_tr_b16 v[220:221], v194 offset:0x1a00
	v_max3_f32 v0, v0, v84, v85
	v_max3_f32 v0, v0, v86, v87
	s_waitcnt lgkmcnt(4)
	v_mfma_f32_32x32x16_bf16 v[50:65], v[174:177], v[222:225], v[50:65]
	ds_read_b64_tr_b16 v[222:223], v194 offset:0x2200
	ds_read_b64_tr_b16 v[224:225], v194 offset:0x2a00
	v_max3_f32 v0, v0, v88, v89
	v_max3_f32 v0, v0, v90, v91
	v_mfma_f32_32x32x16_bf16 v[50:65], v[178:181], v[226:229], v[50:65]
	ds_read_b64_tr_b16 v[226:227], v194 offset:0x3200
	ds_read_b64_tr_b16 v[228:229], v194 offset:0x3a00
	v_max3_f32 v0, v0, v92, v93
	v_max3_f32 v0, v0, v94, v95
	v_max3_f32 v0, v0, v96, v97
	s_waitcnt lgkmcnt(4)
	v_mfma_f32_32x32x16_bf16 v[34:49], v[166:169], v[214:217], v[34:49]
	ds_read_b64_tr_b16 v[214:215], v194 offset:0x400
	ds_read_b64_tr_b16 v[216:217], v194 offset:0xc00
	v_max3_f32 v0, v0, v66, v67
	v_max3_f32 v0, v0, v68, v69
	v_mfma_f32_32x32x16_bf16 v[34:49], v[170:173], v[218:221], v[34:49]
	ds_read_b64_tr_b16 v[218:219], v194 offset:0x1400
	ds_read_b64_tr_b16 v[220:221], v194 offset:0x1c00
	v_max3_f32 v0, v0, v70, v71
	v_max3_f32 v0, v0, v72, v73
	s_waitcnt lgkmcnt(4)
	v_mfma_f32_32x32x16_bf16 v[34:49], v[174:177], v[222:225], v[34:49]
	ds_read_b64_tr_b16 v[222:223], v194 offset:0x2400
	ds_read_b64_tr_b16 v[224:225], v194 offset:0x2c00
	v_max3_f32 v0, v0, v74, v75
	v_max3_f32 v0, v0, v76, v77
	v_max3_f32 v0, v0, v78, v79
	v_mfma_f32_32x32x16_bf16 v[34:49], v[178:181], v[226:229], v[34:49]
	ds_read_b64_tr_b16 v[226:227], v194 offset:0x3400
	ds_read_b64_tr_b16 v[228:229], v194 offset:0x3c00
	v_max3_f32 v0, v0, v80, v81
	v_mov_b32_e32 v190, v0
	s_waitcnt lgkmcnt(4)
	v_mfma_f32_32x32x16_bf16 v[18:33], v[166:169], v[214:217], v[18:33]
	ds_read_b64_tr_b16 v[214:215], v194 offset:0x600
	ds_read_b64_tr_b16 v[216:217], v194 offset:0xe00
	v_permlane32_swap_b32_e32 v0, v190
	v_mfma_f32_32x32x16_bf16 v[18:33], v[170:173], v[218:221], v[18:33]
	ds_read_b64_tr_b16 v[218:219], v194 offset:0x1600
	ds_read_b64_tr_b16 v[220:221], v194 offset:0x1e00
	v_max_f32_e32 v0, v0, v190
	s_waitcnt lgkmcnt(4)
	v_mfma_f32_32x32x16_bf16 v[18:33], v[174:177], v[222:225], v[18:33]
	ds_read_b64_tr_b16 v[222:223], v194 offset:0x2600
	ds_read_b64_tr_b16 v[224:225], v194 offset:0x2e00
	v_sub_f32_e32 v190, v0, v210
	v_mfma_f32_32x32x16_bf16 v[18:33], v[178:181], v[226:229], v[18:33]
	ds_read_b64_tr_b16 v[226:227], v194 offset:0x3600
	ds_read_b64_tr_b16 v[228:229], v194 offset:0x3e00
	s_waitcnt lgkmcnt(4)
	v_mfma_f32_32x32x16_bf16 v[2:17], v[166:169], v[214:217], v[2:17]
	s_waitcnt vmcnt(2)
	v_add_u32_e32 v192, 0x10800, v206
	ds_write_b128 v207, v[154:157] offset:32768
	ds_write_b128 v207, v[158:161] offset:41472
	ds_write_b128 v192, v[162:165]
	v_mul_f32_e32 v190, 0x3d93cd3a, v190
	v_mfma_f32_32x32x16_bf16 v[2:17], v[170:173], v[218:221], v[2:17]
	v_cmp_ge_f32_e32 vcc, 0x41000000, v190
	s_waitcnt lgkmcnt(3)
	v_mfma_f32_32x32x16_bf16 v[2:17], v[174:177], v[222:225], v[2:17]
	s_cmp_eq_u64 vcc, exec
	s_cselect_b64 s[6:7], -1, 0
	v_mfma_f32_32x32x16_bf16 v[2:17], v[178:181], v[226:229], v[2:17]
	s_barrier
	s_waitcnt vmcnt(0)
	ds_write_b128 v202, v[146:149]
	ds_write_b128 v203, v[150:153]
	s_and_b64 vcc, exec, s[6:7]
	s_cbranch_vccnz .Lfast1
	v_max_f32_e32 v0, v210, v0
	v_sub_f32_e32 v191, v210, v0
	v_mul_f32_e32 v191, 0x3dd53b94, v191
	v_exp_f32_e32 v213, v191
	v_mov_b32_e32 v210, v0
	v_cmp_gt_f32_e32 vcc, 1.0, v213
	s_cbranch_vccz .LBB0_414
	s_and_saveexec_b64 s[8:9], s[4:5]
	ds_write_b32 v195, v213 offset:128
	s_or_b64 exec, exec, s[8:9]
	s_waitcnt lgkmcnt(0)
	ds_read_b128 v[166:169], v198 offset:224
	ds_read_b128 v[170:173], v198 offset:192
	ds_read_b128 v[174:177], v198 offset:160
	ds_read_b128 v[178:181], v198 offset:128
	s_waitcnt lgkmcnt(3)
	v_pk_mul_f32 v[64:65], v[64:65], v[168:169]
	s_waitcnt lgkmcnt(2)
	v_pk_mul_f32 v[60:61], v[60:61], v[172:173]
	s_waitcnt lgkmcnt(1)
	v_pk_mul_f32 v[56:57], v[56:57], v[176:177]
	s_waitcnt lgkmcnt(0)
	v_pk_mul_f32 v[52:53], v[52:53], v[180:181]
	v_pk_mul_f32 v[62:63], v[62:63], v[166:167]
	v_pk_mul_f32 v[58:59], v[58:59], v[170:171]
	v_pk_mul_f32 v[54:55], v[54:55], v[174:175]
	v_pk_mul_f32 v[50:51], v[50:51], v[178:179]
	v_pk_mul_f32 v[48:49], v[48:49], v[168:169]
	v_pk_mul_f32 v[44:45], v[44:45], v[172:173]
	v_pk_mul_f32 v[40:41], v[40:41], v[176:177]
	v_pk_mul_f32 v[36:37], v[36:37], v[180:181]
	v_pk_mul_f32 v[46:47], v[46:47], v[166:167]
	v_pk_mul_f32 v[42:43], v[42:43], v[170:171]
	v_pk_mul_f32 v[38:39], v[38:39], v[174:175]
	v_pk_mul_f32 v[34:35], v[34:35], v[178:179]
	v_pk_mul_f32 v[32:33], v[32:33], v[168:169]
	v_pk_mul_f32 v[28:29], v[28:29], v[172:173]
	v_pk_mul_f32 v[24:25], v[24:25], v[176:177]
	v_pk_mul_f32 v[20:21], v[20:21], v[180:181]
	v_pk_mul_f32 v[30:31], v[30:31], v[166:167]
	v_pk_mul_f32 v[26:27], v[26:27], v[170:171]
	v_pk_mul_f32 v[22:23], v[22:23], v[174:175]
	v_pk_mul_f32 v[18:19], v[18:19], v[178:179]
	v_pk_mul_f32 v[16:17], v[16:17], v[168:169]
	v_pk_mul_f32 v[12:13], v[12:13], v[172:173]
	v_pk_mul_f32 v[8:9], v[8:9], v[176:177]
	v_pk_mul_f32 v[4:5], v[4:5], v[180:181]
	v_pk_mul_f32 v[14:15], v[14:15], v[166:167]
	v_pk_mul_f32 v[10:11], v[10:11], v[170:171]
	v_pk_mul_f32 v[6:7], v[6:7], v[174:175]
	v_pk_mul_f32 v[2:3], v[2:3], v[178:179]
	s_branch .LBB0_414

; __device__ __forceinline__ void partialSM(f32x16& p0, f32x16& p1, float& m_reg, float& mn, float& alpha) {
;     float pmax = p0[0];
; #pragma unroll
;     for (int r = 1; r < 16; ++r) pmax = fmaxf(pmax, p0[r]);
; #pragma unroll
;     for (int r = 0; r < 16; ++r) pmax = fmaxf(pmax, p1[r]);
;     { auto rr = __builtin_amdgcn_permlane32_swap(__float_as_uint(pmax), __float_as_uint(pmax), false, false);
;       pmax = fmaxf(__uint_as_float(rr[0]), __uint_as_float(rr[1])); }
; template <int VB>
; __device__ __forceinline__ void pv_tile(f32x16* o, int vb0, bf16x8 pa0, bf16x8 pa1, bf16x8 pa2, bf16x8 pa3) {
;     ...
;     PV_D0(0); PV_D0(1); PV_D0(2); PV_D0(3);
.LBB0_418:
	s_waitcnt lgkmcnt(4)
	v_mfma_f32_32x32x16_bf16 v[50:65], v[166:169], v[218:221], v[50:65]
	ds_read_b64_tr_b16 v[218:219], v194 offset:0x4200
	ds_read_b64_tr_b16 v[220:221], v194 offset:0x4a00
	v_mfma_f32_32x32x16_bf16 v[50:65], v[170:173], v[222:225], v[50:65]
	ds_read_b64_tr_b16 v[222:223], v194 offset:0x5200
	ds_read_b64_tr_b16 v[224:225], v194 offset:0x5a00
	v_max_f32_e32 v0, v82, v83
	v_max3_f32 v0, v0, v84, v85
	s_waitcnt lgkmcnt(4)
	v_mfma_f32_32x32x16_bf16 v[50:65], v[174:177], v[226:229], v[50:65]
	ds_read_b64_tr_b16 v[226:227], v194 offset:0x6200
	ds_read_b64_tr_b16 v[228:229], v194 offset:0x6a00
	v_max3_f32 v0, v0, v86, v87
	v_max3_f32 v0, v0, v88, v89
	v_mfma_f32_32x32x16_bf16 v[50:65], v[178:181], v[230:233], v[50:65]
	ds_read_b64_tr_b16 v[230:231], v194 offset:0x7200
	ds_read_b64_tr_b16 v[232:233], v194 offset:0x7a00
	v_max3_f32 v0, v0, v90, v91
	v_max3_f32 v0, v0, v92, v93
	s_waitcnt lgkmcnt(4)
	v_mfma_f32_32x32x16_bf16 v[34:49], v[166:169], v[218:221], v[34:49]
	ds_read_b64_tr_b16 v[218:219], v194 offset:0x4400
	ds_read_b64_tr_b16 v[220:221], v194 offset:0x4c00
	v_max3_f32 v0, v0, v94, v95
	v_max3_f32 v0, v0, v96, v97
	v_mfma_f32_32x32x16_bf16 v[34:49], v[170:173], v[222:225], v[34:49]
	ds_read_b64_tr_b16 v[222:223], v194 offset:0x5400
	ds_read_b64_tr_b16 v[224:225], v194 offset:0x5c00
	v_max3_f32 v0, v0, v66, v67
	v_max3_f32 v0, v0, v68, v69
	s_waitcnt lgkmcnt(4)
	v_mfma_f32_32x32x16_bf16 v[34:49], v[174:177], v[226:229], v[34:49]
	ds_read_b64_tr_b16 v[226:227], v194 offset:0x6400
	ds_read_b64_tr_b16 v[228:229], v194 offset:0x6c00
	v_max3_f32 v0, v0, v70, v71
	v_max3_f32 v0, v0, v72, v73
	v_mfma_f32_32x32x16_bf16 v[34:49], v[178:181], v[230:233], v[34:49]
	ds_read_b64_tr_b16 v[230:231], v194 offset:0x7400
	ds_read_b64_tr_b16 v[232:233], v194 offset:0x7c00
	v_max3_f32 v0, v0, v74, v75
	v_max3_f32 v0, v0, v76, v77
	s_waitcnt lgkmcnt(4)
	v_mfma_f32_32x32x16_bf16 v[18:33], v[166:169], v[218:221], v[18:33]
	ds_read_b64_tr_b16 v[218:219], v194 offset:0x4600
	ds_read_b64_tr_b16 v[220:221], v194 offset:0x4e00
	v_max3_f32 v0, v0, v78, v79
	v_max3_f32 v0, v0, v80, v81
	v_mfma_f32_32x32x16_bf16 v[18:33], v[170:173], v[222:225], v[18:33]
	ds_read_b64_tr_b16 v[222:223], v194 offset:0x5600
	ds_read_b64_tr_b16 v[224:225], v194 offset:0x5e00
	v_mov_b32_e32 v190, v0
	s_waitcnt lgkmcnt(4)
	v_mfma_f32_32x32x16_bf16 v[18:33], v[174:177], v[226:229], v[18:33]
	ds_read_b64_tr_b16 v[226:227], v194 offset:0x6600
	ds_read_b64_tr_b16 v[228:229], v194 offset:0x6e00
	v_permlane32_swap_b32_e32 v0, v190
	v_mfma_f32_32x32x16_bf16 v[18:33], v[178:181], v[230:233], v[18:33]
	ds_read_b64_tr_b16 v[230:231], v194 offset:0x7600
	ds_read_b64_tr_b16 v[232:233], v194 offset:0x7e00
	v_max_f32_e32 v0, v0, v190
	s_waitcnt lgkmcnt(4)
	v_mfma_f32_32x32x16_bf16 v[2:17], v[166:169], v[218:221], v[2:17]
	s_and_b64 vcc, exec, s[90:91]
	s_cbranch_vccnz .Lkw2_do
	s_waitcnt lgkmcnt(0)
	s_branch .Lkw2_done
